# G6 takes its unit table backwards (reads the ACT rows G5 wrote last first: memory-side cache locality); v75 otherwise
# speedup vs baseline: 1.0020x; 1.0020x over previous
.LBB0_1377:
	s_cmp_lt_i32 s16, 1
	s_cbranch_scc1 .LBB0_1393
	s_lshl_b32 s17, s88, 10
	v_lshl_add_u32 v0, v26, 4, s17
	v_add_u32_e32 v1, 0x2000, v0
	v_ashrrev_i32_e32 v2, 31, v1
	v_lshrrev_b32_e32 v2, 22, v2
	v_add_u32_e32 v2, v1, v2
	v_ashrrev_i32_e32 v8, 10, v2
	v_mul_i32_i24_e32 v2, 0x400, v8
	v_sub_u32_e32 v1, v1, v2
	v_lshrrev_b32_e32 v2, 4, v1
	v_bitop3_b32 v1, v2, v1, 32 bitop3:0x6c
	v_ashrrev_i32_e32 v2, 31, v1
	v_lshrrev_b32_e32 v2, 26, v2
	v_add_u32_e32 v2, v1, v2
	v_ashrrev_i32_e32 v9, 6, v2
	v_lshlrev_b32_e32 v3, 3, v8
	v_and_b32_e32 v2, 0xffc0, v2
	v_and_b32_e32 v3, -16, v3
	v_sub_u32_e32 v1, v1, v2
	v_add_u32_e32 v3, v9, v3
	v_lshrrev_b16_e32 v2, 7, v1
	v_and_b32_e32 v4, 3, v9
	s_mov_b32 s2, 0xffffe0
	v_lshrrev_b32_e32 v5, 2, v3
	v_lshlrev_b32_e32 v6, 1, v3
	v_and_b32_e32 v2, 1, v2
	v_and_or_b32 v4, v3, s2, v4
	v_and_b32_e32 v5, 4, v5
	v_and_b32_e32 v6, 24, v6
	v_add_u16_e32 v1, v1, v2
	v_mov_b32_e32 v2, 1
	v_or3_b32 v4, v4, v5, v6
	v_lshlrev_b32_e32 v5, 5, v8
	v_ashrrev_i16_sdwa v1, v2, sext(v1) dst_sel:DWORD dst_unused:UNUSED_PAD src0_sel:DWORD src1_sel:BYTE_0
	s_movk_i32 s0, 0xb00
	v_and_b32_e32 v10, 32, v5
	v_bfe_i32 v11, v1, 0, 16
	v_mul_u32_u24_e32 v4, 0xb00, v4
	v_add_u32_e32 v1, v10, v11
	v_mul_lo_u32 v3, v3, s0
	v_add_lshl_u32 v160, v4, v1, 1
	v_add_lshl_u32 v162, v1, v3, 1
	v_ashrrev_i32_e32 v1, 31, v0
	v_lshrrev_b32_e32 v1, 22, v1
	v_add_u32_e32 v1, v0, v1
	v_ashrrev_i32_e32 v12, 10, v1
	v_mul_i32_i24_e32 v1, 0x400, v12
	v_sub_u32_e32 v0, v0, v1
	v_lshrrev_b32_e32 v1, 4, v0
	v_bitop3_b32 v0, v1, v0, 32 bitop3:0x6c
	v_ashrrev_i32_e32 v1, 31, v0
	v_lshrrev_b32_e32 v1, 26, v1
	v_add_u32_e32 v1, v0, v1
	v_lshlrev_b32_e32 v3, 3, v12
	s_lshr_b32 s1, s33, 8
	v_ashrrev_i32_e32 v13, 6, v1
	v_and_b32_e32 v3, -16, v3
	v_and_b32_e32 v1, 0xc0, v1
	s_add_u32 s20, s40, 0x2100000
	v_add_u32_e32 v3, v13, v3
	v_and_b32_e32 v4, 3, v13
	v_sub_u32_e32 v0, v0, v1
	s_addc_u32 s21, s41, 0
	v_and_or_b32 v4, v3, s2, v4
	v_ashrrev_i16_sdwa v0, v2, sext(v0) dst_sel:DWORD dst_unused:UNUSED_PAD src0_sel:DWORD src1_sel:BYTE_0
	s_add_i32 s2, 0, 0x20200
	s_add_i32 s99, s16, -1
	s_lshl_b32 s99, s99, 4
	s_add_i32 s2, s2, s99
	v_bfe_i32 v15, v0, 0, 16
	v_mov_b32_e32 v0, s2
	ds_read_b96 v[0:2], v0
	v_lshrrev_b32_e32 v5, 2, v3
	v_lshlrev_b32_e32 v6, 1, v3
	v_and_b32_e32 v5, 4, v5
	v_and_b32_e32 v6, 24, v6
	s_waitcnt lgkmcnt(0)
	v_readfirstlane_b32 s2, v2
	v_readfirstlane_b32 s38, v1
	s_cmp_eq_u32 s2, 0
	v_or3_b32 v4, v4, v5, v6
	v_lshlrev_b32_e32 v5, 5, v12
	s_cselect_b32 s3, s20, 0
	s_mul_i32 s9, s38, 0x160000
	v_and_b32_e32 v14, 32, v5
	s_cselect_b32 s2, s21, 0
	s_mul_hi_i32 s8, s38, 0x160000
	s_cselect_b32 s12, s19, 0
	s_cselect_b32 s13, s18, 0
	s_add_u32 s10, s3, s9
	v_mul_u32_u24_e32 v4, 0xb00, v4
	v_add_u32_e32 v5, v14, v15
	s_addc_u32 s11, s2, s8
	s_add_i32 s22, s17, 0
	v_add_lshl_u32 v164, v4, v5, 1
	s_add_i32 m0, s22, 0x10000
	v_readfirstlane_b32 s39, v0
	global_load_lds_dwordx4 v164, s[10:11]
	s_add_i32 m0, s22, 0x12000
	s_add_u32 s2, s10, 0xb0000
	global_load_lds_dwordx4 v160, s[10:11]
	s_addc_u32 s3, s11, 0
	s_add_i32 m0, s22, 0x14000
	s_mul_i32 s7, s39, 0x160000
	global_load_lds_dwordx4 v164, s[2:3]
	s_add_i32 m0, s22, 0x16000
	s_mul_hi_i32 s6, s39, 0x160000
	s_add_u32 s8, s13, s7
	v_mul_lo_u32 v3, v3, s0
	s_addc_u32 s9, s12, s6
	s_add_i32 s23, s22, 0x2000
	v_add_lshl_u32 v166, v5, v3, 1
	global_load_lds_dwordx4 v160, s[2:3]
	s_mov_b32 m0, s22
	s_add_u32 s2, s8, 0xb0000
	global_load_lds_dwordx4 v166, s[8:9]
	s_mov_b32 m0, s23
	s_addc_u32 s3, s9, 0
	s_add_i32 s24, s22, 0x4000
	global_load_lds_dwordx4 v162, s[8:9]
	s_mov_b32 m0, s24
	s_add_i32 s25, s22, 0x6000
	global_load_lds_dwordx4 v166, s[2:3]
	s_mov_b32 m0, s25
	v_mov_b32_e32 v165, 0
	global_load_lds_dwordx4 v162, s[2:3]
	v_mov_b32_e32 v161, v165
	v_mov_b32_e32 v167, v165
	v_mov_b32_e32 v163, v165
	s_mov_b32 s26, 0
	v_lshl_add_u64 v[6:7], s[10:11], 0, v[164:165]
	v_lshl_add_u64 v[4:5], s[10:11], 0, v[160:161]
	v_lshl_add_u64 v[2:3], s[8:9], 0, v[166:167]
	s_cmp_lg_u32 s1, 1
	v_lshl_add_u64 v[0:1], s[8:9], 0, v[162:163]
	s_cbranch_scc1 .LBB0_1380
	s_barrier

.LBB0_1381:
	s_add_i32 s26, s26, 1
	s_cmp_lt_i32 s26, s16
	s_cselect_b64 s[6:7], -1, 0
	s_cmp_ge_i32 s26, s16
	s_cbranch_scc1 .LBB0_1383
	s_sub_i32 s0, s16, s26
	s_add_i32 s0, s0, -1
	s_lshl_b32 s0, s0, 4
	s_add_i32 s0, s0, 0
	s_add_i32 s0, s0, 0x20200
	v_mov_b32_e32 v0, s0
	ds_read_b96 v[0:2], v0
	s_waitcnt lgkmcnt(0)
	v_readfirstlane_b32 s35, v0
	v_readfirstlane_b32 s36, v1
	v_readfirstlane_b32 s37, v2
